# GEMM tile loop: removed hipcc's full vmcnt(0) drain before each tile's K-loop (the K-loop's own counted waits cover the staged tiles; epilogue stores no longer block the next tile's start)
# speedup vs baseline: 1.0054x; 1.0054x over previous
; DI void gemm_phase(LAS unsigned char* lds, const GemmDesc& d, float* __restrict__ X) {
;     ...
; #pragma unroll
;     for (int a = 0; a < 2; ++a)
; #pragma unroll
;       for (int b = 0; b < 2; ++b)
; #pragma unroll
;         for (int m = 0; m < 4; ++m)
; #pragma unroll
;           for (int n = 0; n < 2; ++n) acc[a][b][m][n] = (f32x4){0.f, 0.f, 0.f, 0.f};
;     pm = pm2; pn = pn2; cA = nA; cB = nB;
.LBB0_345:
	s_or_b64 exec, exec, s[78:79]
	s_add_u32 s20, s88, s27
	s_addc_u32 s21, s89, 0
	s_add_u32 s64, s90, 0x100
	v_mov_b32_e32 v2, 0
	s_addc_u32 s69, s91, 0
	s_mov_b64 s[90:91], 0
	v_mov_b32_e32 v3, v2
	v_mov_b32_e32 v4, v2
	v_mov_b32_e32 v5, v2
	v_mov_b32_e32 v6, v2
	v_mov_b32_e32 v7, v2
	v_mov_b32_e32 v8, v2
	v_mov_b32_e32 v9, v2
	v_mov_b32_e32 v18, v2
	v_mov_b32_e32 v19, v2
	v_mov_b32_e32 v20, v2
	v_mov_b32_e32 v21, v2
	v_mov_b32_e32 v22, v2
	v_mov_b32_e32 v23, v2
	v_mov_b32_e32 v24, v2
	v_mov_b32_e32 v25, v2
	v_mov_b32_e32 v34, v2
	v_mov_b32_e32 v35, v2
	v_mov_b32_e32 v36, v2
	v_mov_b32_e32 v37, v2
	v_mov_b32_e32 v38, v2
	v_mov_b32_e32 v39, v2
	v_mov_b32_e32 v40, v2
	v_mov_b32_e32 v41, v2
	v_mov_b32_e32 v50, v2
	v_mov_b32_e32 v51, v2
	v_mov_b32_e32 v52, v2
	v_mov_b32_e32 v53, v2
	v_mov_b32_e32 v54, v2
	v_mov_b32_e32 v55, v2
	v_mov_b32_e32 v56, v2
	v_mov_b32_e32 v57, v2
	v_mov_b32_e32 v10, v2
	v_mov_b32_e32 v11, v2
	v_mov_b32_e32 v12, v2
	v_mov_b32_e32 v13, v2
	s_nop 0
	v_mov_b32_e32 v14, v2
	v_mov_b32_e32 v15, v2
	v_mov_b32_e32 v16, v2
	v_mov_b32_e32 v17, v2
	v_mov_b32_e32 v26, v2
	v_mov_b32_e32 v27, v2
	v_mov_b32_e32 v28, v2
	v_mov_b32_e32 v29, v2
	v_mov_b32_e32 v30, v2
	v_mov_b32_e32 v31, v2
	v_mov_b32_e32 v32, v2
	v_mov_b32_e32 v33, v2
	v_mov_b32_e32 v42, v2
	v_mov_b32_e32 v43, v2
	v_mov_b32_e32 v44, v2
	v_mov_b32_e32 v45, v2
	v_mov_b32_e32 v46, v2
	v_mov_b32_e32 v47, v2
	v_mov_b32_e32 v48, v2
	v_mov_b32_e32 v49, v2
	v_mov_b32_e32 v58, v2
	v_mov_b32_e32 v59, v2
	v_mov_b32_e32 v60, v2
	v_mov_b32_e32 v61, v2
	v_mov_b32_e32 v62, v2
	v_mov_b32_e32 v63, v2
	v_mov_b32_e32 v64, v2
	v_mov_b32_e32 v65, v2
	v_mov_b32_e32 v66, v2
	v_mov_b32_e32 v67, v2
	v_mov_b32_e32 v68, v2
	v_mov_b32_e32 v69, v2
	v_mov_b32_e32 v70, v2
	v_mov_b32_e32 v71, v2
	v_mov_b32_e32 v72, v2
	v_mov_b32_e32 v73, v2
	v_mov_b32_e32 v82, v2
	v_mov_b32_e32 v83, v2
	v_mov_b32_e32 v84, v2
	v_mov_b32_e32 v85, v2
	v_mov_b32_e32 v86, v2
	v_mov_b32_e32 v87, v2
	v_mov_b32_e32 v88, v2
	v_mov_b32_e32 v89, v2
	v_mov_b32_e32 v98, v2
	v_mov_b32_e32 v99, v2
	v_mov_b32_e32 v100, v2
	v_mov_b32_e32 v101, v2
	v_mov_b32_e32 v102, v2
	v_mov_b32_e32 v103, v2
	v_mov_b32_e32 v104, v2
	v_mov_b32_e32 v105, v2
	v_mov_b32_e32 v114, v2
	v_mov_b32_e32 v115, v2
	v_mov_b32_e32 v116, v2
	v_mov_b32_e32 v117, v2
	v_mov_b32_e32 v118, v2
	v_mov_b32_e32 v119, v2
	v_mov_b32_e32 v120, v2
	v_mov_b32_e32 v121, v2
	v_mov_b32_e32 v74, v2
	v_mov_b32_e32 v75, v2
	v_mov_b32_e32 v76, v2
	v_mov_b32_e32 v77, v2
	v_mov_b32_e32 v78, v2
	v_mov_b32_e32 v79, v2
	v_mov_b32_e32 v80, v2
	v_mov_b32_e32 v81, v2
	v_mov_b32_e32 v90, v2
	v_mov_b32_e32 v91, v2
	v_mov_b32_e32 v92, v2
	v_mov_b32_e32 v93, v2
	v_mov_b32_e32 v94, v2
	v_mov_b32_e32 v95, v2
	v_mov_b32_e32 v96, v2
	v_mov_b32_e32 v97, v2
	v_mov_b32_e32 v106, v2
	v_mov_b32_e32 v107, v2
	v_mov_b32_e32 v108, v2
	v_mov_b32_e32 v109, v2
	v_mov_b32_e32 v110, v2
	v_mov_b32_e32 v111, v2
	v_mov_b32_e32 v112, v2
	v_mov_b32_e32 v113, v2
	v_mov_b32_e32 v122, v2
	v_mov_b32_e32 v123, v2
	v_mov_b32_e32 v124, v2
	v_mov_b32_e32 v125, v2
	v_mov_b32_e32 v126, v2
	v_mov_b32_e32 v127, v2
	v_mov_b32_e32 v128, v2
	v_mov_b32_e32 v129, v2
